# GQA loop rewritten as role-alternating halves (waves 0-3 / 4-7 one barrier interval apart; bare-MFMA QK and PV segments with LDS reads in the MFMA gaps, softmax and DMA segments beside the partner's M
# speedup vs baseline: 1.0111x; 1.0094x over previous
; __device__ __forceinline__ int v_rd_base(int lane) { return ((lane & 3) << 3) | (((lane >> 2) & 3) << 6) | (((lane >> 4) & 1) << 5) | (((lane >> 5) & 1) << 8); }
; #define NAM(P0, P1, t) do { if constexpr (NA) na_mask(P0, P1, kr_lo + (t), r0, qrow, qc, c0, hi, bl); } while (0)
; #define PSM(P0, P1, MN, AL) do { if constexpr (NA) partialSM(P0, P1, m_reg, MN, AL); else { AL = 1.f; _Pragma("unroll") for (int r = 0; r < 16; ++r) P0[r] = __builtin_amdgcn_exp2f(P0[r]); } } while (0)
; #define VM0() asm volatile("s_waitcnt vmcnt(0)" ::: "memory")
; #define NAM(P0, P1, t) do { if constexpr (NA) na_mask(P0, P1, kr_lo + (t), r0, qrow, qc, c0, hi, bl); } while (0)
; template <bool NA, int ROWB>
; __device__ __forceinline__ void attn_dma(const bf16* __restrict__ Qb, const bf16* __restrict__ Kh, const bf16* __restrict__ Vh, bf16* __restrict__ Ob, int NT, char* lds, const int tid, float* __restrict__ ssb, int qrow0, int kr_lo, const float* bl) {
;     ...
;   float m_reg = -1e30f, l_reg = 0; f32x16 o[4] = {}; bf16x8 qr[8];
;   const int qrow = qrow0 + (wid >> 1), qc = 32 * (wid & 1) + r32;
;   const int c0 = min(max(qc - 8, 0), 48), r0 = min(max(qrow - 4, 0), 120);
;   const bf16* Qw = Qb + (long)(wid * QBLK + r32) * LDQ + hi * 8;
; #pragma unroll
;   for (int d0 = 0; d0 < 8; ++d0) qr[d0] = *reinterpret_cast<const bf16x8*>(Qw + d0 * 16);
;   const int vb0 = (int)(uintptr_t)V_lds + v_rd_base(lane);
;   auto src_off = [&](int i, unsigned& ko, unsigned& vo) __attribute__((always_inline)) {
;     const int b = (wid * 2 + i) * 1024 + lane * 16;
;     { const int row = b >> 8, cb = (b & 255) ^ ((row & 7) << 4); ko = (unsigned)(row * ROWB + cb); }
;     { const int st = b >> 9, within = b & 511, kk = (st >> 2) * 8 + (within >> 6), c = (st & 3) * 32 + ((within & 63) >> 1);
;       const int k = (kk & ~0xC) | ((kk & 4) << 1) | ((kk & 8) >> 1); vo = (unsigned)(k * ROWB + c * 2); }
;   };
;   unsigned ksrc[2], vsrc[2];
;   if constexpr (!NA) { src_off(0, ksrc[0], vsrc[0]); src_off(1, ksrc[1], vsrc[1]); }
;     ...
;   f32x16 pA0, pA1, pB0, pB1; bf16x8 pa0, pa1, pa2, pa3; float mnA, mnB, alA, alB;
;   DMA_TILE(0, 0); DMA_TILE(1, 1); VM0(); __syncthreads();
;   qkt<false>(pA0, pA1, (const bf16*)K_lds, qr, nullptr, r32, hi); NAM(pA0, pA1, 0); PSM(pA0, pA1, mnA, alA);
.LBB0_105:
	s_lshl_b32 s0, s22, 19
	s_and_b32 s0, s0, 0x200000
	v_readlane_b32 s4, v254, 32
	v_readlane_b32 s5, v254, 33
	s_add_u32 s18, s4, s0
	s_addc_u32 s19, s5, 0
	s_lshl_b32 s0, s23, 5
	s_and_b32 s6, s0, 0xffffff00
	s_and_b32 s14, s23, 7
	s_ashr_i32 s7, s6, 31
	s_mul_i32 s1, s6, 0x2400
	s_mul_hi_i32 s0, s6, 0x2400
	s_add_u32 s1, s16, s1
	s_addc_u32 s4, s17, s0
	s_lshl_b32 s15, s14, 7
	s_lshl_b32 s0, s14, 8
	s_add_u32 s0, s1, s0
	s_addc_u32 s1, s4, 0
	s_waitcnt lgkmcnt(0)
	v_lshl_add_u64 v[0:1], s[0:1], 0, v[162:163]
	v_mov_b32_e32 v175, v113
	v_lshl_add_u64 v[0:1], v[0:1], 0, v[174:175]
	s_movk_i32 s0, 0x1000
	v_add_co_u32_e64 v2, s[4:5], s0, v0
	s_nop 1
	v_addc_co_u32_e64 v3, s[4:5], 0, v1, s[4:5]
	s_barrier
	global_load_dwordx4 v[138:141], v[2:3], off offset:2048
	s_mov_b64 s[4:5], 0x1800
	v_lshl_add_u64 v[0:1], v[0:1], 0, s[4:5]
	global_load_dwordx4 v[142:145], v[0:1], off offset:32
	global_load_dwordx4 v[134:137], v[0:1], off offset:64
	global_load_dwordx4 v[114:117], v[0:1], off offset:96
	global_load_dwordx4 v[118:121], v[0:1], off offset:128
	global_load_dwordx4 v[122:125], v[0:1], off offset:160
	global_load_dwordx4 v[126:129], v[0:1], off offset:192
	global_load_dwordx4 v[130:133], v[0:1], off offset:224
	s_lshl_b32 s0, s23, 19
	s_and_b32 s16, s0, 0x200000
	s_add_u32 s0, s12, s16
	s_addc_u32 s1, s13, 0
	s_add_u32 s16, s8, s16
	v_readfirstlane_b32 s4, v184
	s_addc_u32 s17, s9, 0
	s_lshr_b32 s98, s23, 3
	s_lshl_b32 s98, s98, 16
	s_add_u32 s0, s0, s98
	s_addc_u32 s1, s1, 0
	s_add_u32 s16, s16, s98
	s_addc_u32 s17, s17, 0
	s_lshl_b32 s4, s4, 11
	s_add_i32 s5, s4, 0
	v_lshl_add_u64 v[0:1], s[0:1], 0, v[164:165]
	s_add_i32 m0, s5, 0xc000
	v_add_u32_e32 v4, 0, v187
	global_load_lds_dwordx4 v[0:1], off
	v_lshl_add_u64 v[0:1], s[16:17], 0, v[166:167]
	s_mov_b32 m0, s5
	v_add_u32_e32 v8, 0, v188
	global_load_lds_dwordx4 v[0:1], off
	v_lshl_add_u64 v[0:1], s[0:1], 0, v[168:169]
	s_add_i32 m0, s5, 0xc400
	v_add_u32_e32 v12, 0, v194
	global_load_lds_dwordx4 v[0:1], off
	s_add_i32 m0, s5, 0x400
	s_add_u32 s0, s0, 0x4000
	s_addc_u32 s1, s1, 0
	v_lshl_add_u64 v[0:1], s[16:17], 0, v[170:171]
	s_add_u32 s16, s16, 0x4000
	global_load_lds_dwordx4 v[0:1], off
	s_addc_u32 s17, s17, 0
	v_lshl_add_u64 v[0:1], s[0:1], 0, v[164:165]
	s_add_i32 m0, s5, 0x10000
	v_mov_b32_e32 v112, 0
	global_load_lds_dwordx4 v[0:1], off
	v_lshl_add_u64 v[0:1], s[16:17], 0, v[166:167]
	s_add_i32 m0, s5, 0x4000
	s_mov_b32 s38, s36
	global_load_lds_dwordx4 v[0:1], off
	v_lshl_add_u64 v[0:1], s[0:1], 0, v[168:169]
	s_add_i32 m0, s5, 0x10400
	s_mov_b32 s0, 1
	global_load_lds_dwordx4 v[0:1], off
	v_lshl_add_u64 v[0:1], s[16:17], 0, v[170:171]
	s_add_i32 m0, s5, 0x4400
	s_mov_b32 s24, 0
	global_load_lds_dwordx4 v[0:1], off
	s_waitcnt vmcnt(0)
	s_waitcnt vmcnt(0) lgkmcnt(0)
	s_barrier
	ds_read_b128 v[0:3], v4 offset:49152
	ds_read_b128 v[4:7], v4 offset:57344
	s_mov_b32 s17, 2
	s_mov_b32 s16, -1
	v_mov_b32_e32 v13, v112
	s_waitcnt lgkmcnt(1)
	v_mfma_f32_32x32x16_bf16 v[14:29], v[0:3], v[138:141], 0
	v_mov_b32_e32 v34, v112
	v_mov_b32_e32 v35, v112
	v_mov_b32_e32 v36, v112
	v_mov_b32_e32 v37, v112
	v_mov_b32_e32 v38, v112
	v_mov_b32_e32 v39, v112
	v_mov_b32_e32 v40, v112
	s_waitcnt lgkmcnt(0)
	v_mfma_f32_32x32x16_bf16 v[64:79], v[4:7], v[138:141], 0
	ds_read_b128 v[0:3], v8 offset:49152
	ds_read_b128 v[4:7], v8 offset:57344
	v_add_u32_e32 v8, 0, v189
	v_mov_b32_e32 v41, v112
	v_mov_b32_e32 v42, v112
	v_mov_b32_e32 v43, v112
	v_mov_b32_e32 v44, v112
	v_mov_b32_e32 v45, v112
	s_waitcnt lgkmcnt(1)
	v_mfma_f32_32x32x16_bf16 v[14:29], v[0:3], v[142:145], v[14:29]
	v_mov_b32_e32 v46, v112
	v_mov_b32_e32 v47, v112
	v_mov_b32_e32 v48, 0
	v_mov_b32_e32 v49, v112
	v_mov_b32_e32 v50, v112
	v_mov_b32_e32 v51, v112
	v_mov_b32_e32 v52, v112
	s_waitcnt lgkmcnt(0)
	v_mfma_f32_32x32x16_bf16 v[64:79], v[4:7], v[142:145], v[64:79]
	ds_read_b128 v[0:3], v8 offset:49152
	ds_read_b128 v[4:7], v8 offset:57344
	v_add_u32_e32 v8, 0, v190
	v_mov_b32_e32 v53, v112
	v_mov_b32_e32 v54, v112
	v_mov_b32_e32 v55, v112
	v_mov_b32_e32 v56, v112
	v_mov_b32_e32 v57, v112
	s_waitcnt lgkmcnt(1)
	v_mfma_f32_32x32x16_bf16 v[14:29], v[0:3], v[134:137], v[14:29]
	v_mov_b32_e32 v58, v112
	v_mov_b32_e32 v59, v112
	v_mov_b32_e32 v60, v112
	v_mov_b32_e32 v61, v112
	v_mov_b32_e32 v62, v112
	v_mov_b32_e32 v63, v112
	s_mov_b64 s[28:29], 0x25d48000
	s_waitcnt lgkmcnt(0)
	v_mfma_f32_32x32x16_bf16 v[64:79], v[4:7], v[134:137], v[64:79]
	ds_read_b128 v[0:3], v8 offset:49152
	ds_read_b128 v[4:7], v8 offset:57344
	v_add_u32_e32 v8, 0, v191
	s_mov_b64 s[36:37], 0x26148000
	s_mov_b64 s[40:41], 0x25d4c000
	s_mov_b64 s[42:43], 0x2614c000
	s_waitcnt lgkmcnt(1)
	v_mfma_f32_32x32x16_bf16 v[14:29], v[0:3], v[114:117], v[14:29]
	s_waitcnt lgkmcnt(0)
	v_mfma_f32_32x32x16_bf16 v[64:79], v[4:7], v[114:117], v[64:79]
	ds_read_b128 v[0:3], v8 offset:49152
	ds_read_b128 v[4:7], v8 offset:57344
	v_add_u32_e32 v8, 0, v192
	s_waitcnt lgkmcnt(1)
	v_mfma_f32_32x32x16_bf16 v[14:29], v[0:3], v[118:121], v[14:29]
	s_waitcnt lgkmcnt(0)
	v_mfma_f32_32x32x16_bf16 v[64:79], v[4:7], v[118:121], v[64:79]
	ds_read_b128 v[0:3], v8 offset:49152
	ds_read_b128 v[4:7], v8 offset:57344
	v_add_u32_e32 v8, 0, v193
	s_waitcnt lgkmcnt(1)
	v_mfma_f32_32x32x16_bf16 v[14:29], v[0:3], v[122:125], v[14:29]
	s_waitcnt lgkmcnt(0)
	v_mfma_f32_32x32x16_bf16 v[64:79], v[4:7], v[122:125], v[64:79]
	ds_read_b128 v[0:3], v8 offset:49152
	ds_read_b128 v[4:7], v8 offset:57344
	ds_read_b128 v[8:11], v12 offset:49152
	ds_read_b128 v[30:33], v12 offset:57344
	v_mov_b32_e32 v12, v112
	s_waitcnt lgkmcnt(3)
; #define SBAR() __builtin_amdgcn_sched_barrier(0)
; #define NAM(P0, P1, t) do { if constexpr (NA) na_mask(P0, P1, kr_lo + (t), r0, qrow, qc, c0, hi, bl); } while (0)
; #define PSM(P0, P1, MN, AL) do { if constexpr (NA) partialSM(P0, P1, m_reg, MN, AL); else { AL = 1.f; _Pragma("unroll") for (int r = 0; r < 16; ++r) P0[r] = __builtin_amdgcn_exp2f(P0[r]); } } while (0)
; #define RESCN(a) do { if constexpr (NA) RESC(a); } while (0)
; #define VM0() asm volatile("s_waitcnt vmcnt(0)" ::: "memory")
; #define NAM(P0, P1, t) do { if constexpr (NA) na_mask(P0, P1, kr_lo + (t), r0, qrow, qc, c0, hi, bl); } while (0)
; #define PSM(P0, P1, MN, AL) do { if constexpr (NA) partialSM(P0, P1, m_reg, MN, AL); else { AL = 1.f; _Pragma("unroll") for (int r = 0; r < 16; ++r) P0[r] = __builtin_amdgcn_exp2f(P0[r]); } } while (0)
; #define RESCN(a) do { if constexpr (NA) RESC(a); } while (0)
; __device__ __forceinline__ void finishSM(f32x16& p0, f32x16& p1, float alpha, float& l_reg, bf16x8& pa0, bf16x8& pa1, bf16x8& pa2, bf16x8& pa3) {
;   for (int r = 0; r < 16; ++r) p1[r] = __builtin_amdgcn_exp2f(p1[r]);
;   float ps = 0; for (int r = 0; r < 16; ++r) ps += p0[r]; for (int r = 0; r < 16; ++r) ps += p1[r];
;   { auto rr = __builtin_amdgcn_permlane32_swap(__float_as_uint(ps), __float_as_uint(ps), false, false);
;     ps = __uint_as_float(rr[0]) + __uint_as_float(rr[1]); }
;   l_reg = l_reg * alpha + ps;
;     ...
;   PK4(p0, 0, pa0); PK4(p0, 8, pa1); PK4(p1, 0, pa2); PK4(p1, 8, pa3);
; template <bool NA, int ROWB>
; __device__ __forceinline__ void attn_dma(const bf16* __restrict__ Qb, const bf16* __restrict__ Kh, const bf16* __restrict__ Vh, bf16* __restrict__ Ob, int NT, char* lds, const int tid, float* __restrict__ ssb, int qrow0, int kr_lo, const float* bl) {
;     ...
;   DMA_TILE(0, 0); DMA_TILE(1, 1); VM0(); __syncthreads();
;   qkt<false>(pA0, pA1, (const bf16*)K_lds, qr, nullptr, r32, hi); NAM(pA0, pA1, 0); PSM(pA0, pA1, mnA, alA);
;   int bp = 0, bc = 1, bn = 2;
;   for (int t = 1; t + 1 < NT; t += 2) {
;     DMA_TILE(t + 1, bn);
;     SBAR(); qkt<false>(pB0, pB1, (const bf16*)(K_lds + bc * SHM_K), qr, nullptr, r32, hi); NAM(pB0, pB1, t);
;     finishSM(pA0, pA1, alA, l_reg, pa0, pa1, pa2, pa3); SBAR();
;     pv_d0(o, vb0 + bp * (int)SHM_V, pa0, pa1, pa2, pa3); PSM(pB0, pB1, mnB, alB); RESCN(alB);
	v_mfma_f32_32x32x16_bf16 v[14:29], v[0:3], v[126:129], v[14:29]
	v_mov_b32_e32 v0, 0
	v_mov_b32_e32 v1, v112
	v_mov_b32_e32 v2, v112
	v_mov_b32_e32 v3, v112
	s_waitcnt lgkmcnt(2)
	v_mfma_f32_32x32x16_bf16 v[64:79], v[4:7], v[126:129], v[64:79]
	v_mov_b32_e32 v4, v112
	v_mov_b32_e32 v5, v112
	v_mov_b32_e32 v6, v112
	v_mov_b32_e32 v7, v112
	s_waitcnt lgkmcnt(1)
	v_mfma_f32_32x32x16_bf16 v[14:29], v[8:11], v[130:133], v[14:29]
	v_mov_b32_e32 v8, v112
	v_mov_b32_e32 v9, v112
	v_mov_b32_e32 v10, v112
	v_mov_b32_e32 v11, v112
	s_waitcnt lgkmcnt(0)
	v_mfma_f32_32x32x16_bf16 v[64:79], v[30:33], v[130:133], v[64:79]
	s_nop 5
	v_exp_f32_e32 v212, v14
	v_exp_f32_e32 v214, v15
	v_exp_f32_e32 v210, v16
	v_exp_f32_e32 v213, v17
	v_exp_f32_e32 v208, v18
	v_exp_f32_e32 v211, v19
	v_exp_f32_e32 v207, v20
	v_exp_f32_e32 v209, v21
	v_exp_f32_e32 v203, v22
	v_exp_f32_e32 v206, v23
	v_exp_f32_e32 v198, v24
	v_exp_f32_e32 v205, v25
	v_exp_f32_e32 v196, v26
	v_exp_f32_e32 v199, v27
	v_exp_f32_e32 v175, v28
	v_exp_f32_e32 v197, v29
	v_mov_b32_e32 v14, v112
	v_mov_b32_e32 v15, v112
	v_mov_b32_e32 v16, 0
	v_mov_b32_e32 v17, v112
	v_mov_b32_e32 v18, v112
	v_mov_b32_e32 v19, v112
	v_mov_b32_e32 v20, v112
	v_mov_b32_e32 v21, v112
	v_mov_b32_e32 v22, v112
	v_mov_b32_e32 v23, v112
	v_mov_b32_e32 v24, v112
	v_mov_b32_e32 v25, v112
	v_mov_b32_e32 v26, v112
	v_mov_b32_e32 v27, v112
	v_mov_b32_e32 v28, v112
	v_mov_b32_e32 v29, v112
	v_mov_b32_e32 v30, v112
	v_mov_b32_e32 v31, v112
	v_mov_b32_e32 v32, 0
	v_mov_b32_e32 v33, v112
	s_mov_b32 s24, 0
	s_mov_b32 s0, 0x4000
	s_mov_b32 s17, 0x8000
	s_add_u32 s40, s18, s28
	s_addc_u32 s41, s19, s29
	s_sub_u32 s40, s40, 0x8000
	s_subb_u32 s41, s41, 0
	s_add_u32 s42, s18, s36
	s_addc_u32 s43, s19, s37
	s_sub_u32 s42, s42, 0x8000
	s_subb_u32 s43, s43, 0
	s_add_u32 s18, s98, 0x8000
	s_mov_b32 s16, 0
	s_cmp_ge_u32 s4, 0x2000
	s_cbranch_scc0 .Lgqa_lead
	s_barrier
.Lgqa_lead:
	v_mov_b32_e32 v80, v212
	v_mov_b32_e32 v81, v214
	v_mov_b32_e32 v82, v210
	v_mov_b32_e32 v83, v213
	v_mov_b32_e32 v84, v208
	v_mov_b32_e32 v85, v211
	v_mov_b32_e32 v86, v207
	v_mov_b32_e32 v87, v209
	v_mov_b32_e32 v88, v203
	v_mov_b32_e32 v89, v206
	v_mov_b32_e32 v90, v198
	v_mov_b32_e32 v91, v205
	v_mov_b32_e32 v92, v196
	v_mov_b32_e32 v93, v199
	v_mov_b32_e32 v94, v175
	v_mov_b32_e32 v95, v197
	v_add_u32_e32 v215, s24, v195
	ds_read_b64_tr_b16 v[146:147], v215 offset:0
	ds_read_b64_tr_b16 v[148:149], v215 offset:2048
	ds_read_b64_tr_b16 v[150:151], v215 offset:4096
	ds_read_b64_tr_b16 v[152:153], v215 offset:6144
	ds_read_b64_tr_b16 v[154:155], v215 offset:8192
	ds_read_b64_tr_b16 v[156:157], v215 offset:10240
	ds_read_b64_tr_b16 v[158:159], v215 offset:12288
	ds_read_b64_tr_b16 v[160:161], v215 offset:14336
	ds_read_b64_tr_b16 v[176:177], v215 offset:512
	ds_read_b64_tr_b16 v[178:179], v215 offset:2560
	ds_read_b64_tr_b16 v[180:181], v215 offset:4608
	ds_read_b64_tr_b16 v[182:183], v215 offset:6656
	ds_read_b64_tr_b16 v[216:217], v215 offset:8704
	ds_read_b64_tr_b16 v[218:219], v215 offset:10752
	ds_read_b64_tr_b16 v[220:221], v215 offset:12800
	ds_read_b64_tr_b16 v[222:223], v215 offset:14848
	ds_read_b64_tr_b16 v[224:225], v215 offset:1024
	ds_read_b64_tr_b16 v[226:227], v215 offset:3072
	ds_read_b64_tr_b16 v[234:235], v215 offset:5120
	ds_read_b64_tr_b16 v[236:237], v215 offset:7168
	ds_read_b64_tr_b16 v[240:241], v215 offset:9216
	ds_read_b64_tr_b16 v[242:243], v215 offset:11264
	ds_read_b64_tr_b16 v[244:245], v215 offset:13312
	ds_read_b64_tr_b16 v[246:247], v215 offset:15360
	ds_read_b64_tr_b16 v[248:249], v215 offset:1536
	ds_read_b64_tr_b16 v[250:251], v215 offset:3584
	ds_read_b64_tr_b16 v[196:197], v215 offset:5632
	ds_read_b64_tr_b16 v[198:199], v215 offset:7680
	ds_read_b64_tr_b16 v[206:207], v215 offset:9728
	ds_read_b64_tr_b16 v[208:209], v215 offset:11776
	ds_read_b64_tr_b16 v[210:211], v215 offset:13824
	ds_read_b64_tr_b16 v[212:213], v215 offset:15872
	v_add_u32_e32 v229, s0, v187
	v_add_u32_e32 v230, s0, v188
	v_add_u32_e32 v232, s0, v189
	v_add_u32_e32 v238, s0, v190
	v_add_u32_e32 v203, s0, v191
	v_add_u32_e32 v205, s0, v192
	v_add_u32_e32 v214, s0, v193
	v_add_u32_e32 v175, s0, v194
	v_exp_f32_e32 v64, v64
	v_exp_f32_e32 v65, v65
	v_exp_f32_e32 v66, v66
	v_exp_f32_e32 v67, v67
	v_exp_f32_e32 v68, v68
	v_exp_f32_e32 v69, v69
	v_exp_f32_e32 v70, v70
	v_exp_f32_e32 v71, v71
	v_exp_f32_e32 v72, v72
	v_exp_f32_e32 v73, v73
	v_exp_f32_e32 v74, v74
	v_exp_f32_e32 v75, v75
	v_exp_f32_e32 v76, v76
	v_exp_f32_e32 v77, v77
	v_exp_f32_e32 v78, v78
	v_exp_f32_e32 v79, v79
	v_cvt_pk_bf16_f32 v96, v80, v81
	v_cvt_pk_bf16_f32 v97, v82, v83
	v_cvt_pk_bf16_f32 v98, v84, v85
	v_cvt_pk_bf16_f32 v99, v86, v87
	v_cvt_pk_bf16_f32 v100, v88, v89
	v_cvt_pk_bf16_f32 v101, v90, v91
	v_cvt_pk_bf16_f32 v102, v92, v93
	v_cvt_pk_bf16_f32 v103, v94, v95
	v_cvt_pk_bf16_f32 v104, v64, v65
	v_cvt_pk_bf16_f32 v105, v66, v67
	v_cvt_pk_bf16_f32 v106, v68, v69
	v_cvt_pk_bf16_f32 v107, v70, v71
	v_cvt_pk_bf16_f32 v108, v72, v73
	v_cvt_pk_bf16_f32 v109, v74, v75
	v_cvt_pk_bf16_f32 v110, v76, v77
	v_cvt_pk_bf16_f32 v111, v78, v79
	s_add_u32 s98, s40, s18
	s_addc_u32 s99, s41, 0
	s_add_i32 s25, s17, s4
	s_add_i32 m0, s25, 0xc000
	s_nop 0
	global_load_lds_dwordx4 v164, s[98:99]
	s_add_i32 m0, s25, 0xc400
	s_nop 0
	global_load_lds_dwordx4 v168, s[98:99]
	s_waitcnt lgkmcnt(0)
	s_barrier
; #define SBAR() __builtin_amdgcn_sched_barrier(0)
; #define NAM(P0, P1, t) do { if constexpr (NA) na_mask(P0, P1, kr_lo + (t), r0, qrow, qc, c0, hi, bl); } while (0)
; #define PSM(P0, P1, MN, AL) do { if constexpr (NA) partialSM(P0, P1, m_reg, MN, AL); else { AL = 1.f; _Pragma("unroll") for (int r = 0; r < 16; ++r) P0[r] = __builtin_amdgcn_exp2f(P0[r]); } } while (0)
; #define RESCN(a) do { if constexpr (NA) RESC(a); } while (0)
; #define VM0() asm volatile("s_waitcnt vmcnt(0)" ::: "memory")
; #define NAM(P0, P1, t) do { if constexpr (NA) na_mask(P0, P1, kr_lo + (t), r0, qrow, qc, c0, hi, bl); } while (0)
; template <bool QL>
; __device__ __forceinline__ void qkt(f32x16& p0, f32x16& p1, const bf16* Ks, const bf16x8* qr, const char* ql, int r32, int hi) {
;   p0 = f32x16{}; p1 = f32x16{};
;   for (int d0 = 0; d0 < 8; ++d0) { int cb = (d0 * 16 + hi * 8) * 2;
;     bf16x8 b0 = *reinterpret_cast<const bf16x8*>((const char*)Ks + KSWZ(r32, cb));
;     bf16x8 b1 = *reinterpret_cast<const bf16x8*>((const char*)Ks + KSWZ(32 + r32, cb));
;     bf16x8 q; if constexpr (QL) q = *reinterpret_cast<const bf16x8*>(ql + d0 * 1024); else q = qr[d0];
;     p0 = __builtin_amdgcn_mfma_f32_32x32x16_bf16(b0, q, p0, 0, 0, 0);
;     p1 = __builtin_amdgcn_mfma_f32_32x32x16_bf16(b1, q, p1, 0, 0, 0); }
; }
; template <bool NA, int ROWB>
; __device__ __forceinline__ void attn_dma(const bf16* __restrict__ Qb, const bf16* __restrict__ Kh, const bf16* __restrict__ Vh, bf16* __restrict__ Ob, int NT, char* lds, const int tid, float* __restrict__ ssb, int qrow0, int kr_lo, const float* bl) {
;     ...
;   for (int t = 1; t + 1 < NT; t += 2) {
;     DMA_TILE(t + 1, bn);
;     SBAR(); qkt<false>(pB0, pB1, (const bf16*)(K_lds + bc * SHM_K), qr, nullptr, r32, hi); NAM(pB0, pB1, t);
;     finishSM(pA0, pA1, alA, l_reg, pa0, pa1, pa2, pa3); SBAR();
;     pv_d0(o, vb0 + bp * (int)SHM_V, pa0, pa1, pa2, pa3); PSM(pB0, pB1, mnB, alB); RESCN(alB);
;     VM0(); __syncthreads();
;     bp = bc; bc = bn; bn = NEXTB(bn);
;     if (t + 2 < NT) DMA_TILE(t + 2, bn);
;     SBAR(); qkt<false>(pA0, pA1, (const bf16*)(K_lds + bc * SHM_K), qr, nullptr, r32, hi); NAM(pA0, pA1, t + 1);
;     finishSM(pB0, pB1, alB, l_reg, pa0, pa1, pa2, pa3); SBAR();
;     pv_d0(o, vb0 + bp * (int)SHM_V, pa0, pa1, pa2, pa3); PSM(pA0, pA1, mnA, alA); RESCN(alA);
;     VM0(); __syncthreads();
	s_setprio 1
	v_mfma_f32_32x32x16_bf16 v[0:15], v[96:99], v[146:149], v[0:15]
	ds_read_b128 v[146:149], v229 offset:49152
	v_mfma_f32_32x32x16_bf16 v[0:15], v[100:103], v[150:153], v[0:15]
	ds_read_b128 v[150:153], v229 offset:57344
	v_mfma_f32_32x32x16_bf16 v[0:15], v[104:107], v[154:157], v[0:15]
	ds_read_b128 v[154:157], v230 offset:49152
	v_mfma_f32_32x32x16_bf16 v[0:15], v[108:111], v[158:161], v[0:15]
	ds_read_b128 v[158:161], v230 offset:57344
	v_mfma_f32_32x32x16_bf16 v[16:31], v[96:99], v[176:179], v[16:31]
	ds_read_b128 v[176:179], v232 offset:49152
	v_mfma_f32_32x32x16_bf16 v[16:31], v[100:103], v[180:183], v[16:31]
	ds_read_b128 v[180:183], v232 offset:57344
	v_mfma_f32_32x32x16_bf16 v[16:31], v[104:107], v[216:219], v[16:31]
	ds_read_b128 v[216:219], v238 offset:49152
	v_mfma_f32_32x32x16_bf16 v[16:31], v[108:111], v[220:223], v[16:31]
	ds_read_b128 v[220:223], v238 offset:57344
	v_mfma_f32_32x32x16_bf16 v[32:47], v[96:99], v[224:227], v[32:47]
	ds_read_b128 v[224:227], v203 offset:49152
	v_mfma_f32_32x32x16_bf16 v[32:47], v[100:103], v[234:237], v[32:47]
	ds_read_b128 v[234:237], v203 offset:57344
	v_mfma_f32_32x32x16_bf16 v[32:47], v[104:107], v[240:243], v[32:47]
	ds_read_b128 v[240:243], v205 offset:49152
	v_mfma_f32_32x32x16_bf16 v[32:47], v[108:111], v[244:247], v[32:47]
	ds_read_b128 v[244:247], v205 offset:57344
	v_mfma_f32_32x32x16_bf16 v[48:63], v[96:99], v[248:251], v[48:63]
	ds_read_b128 v[248:251], v214 offset:49152
	v_mfma_f32_32x32x16_bf16 v[48:63], v[100:103], v[196:199], v[48:63]
	ds_read_b128 v[196:199], v214 offset:57344
	v_mfma_f32_32x32x16_bf16 v[48:63], v[104:107], v[206:209], v[48:63]
	ds_read_b128 v[206:209], v175 offset:49152
	v_mfma_f32_32x32x16_bf16 v[48:63], v[108:111], v[210:213], v[48:63]
	ds_read_b128 v[210:213], v175 offset:57344
	s_setprio 0
	s_waitcnt vmcnt(0)
	s_barrier
	v_add_f32_e32 v112, v80, v112
	v_add_f32_e32 v112, v81, v112
	v_add_f32_e32 v112, v82, v112
	v_add_f32_e32 v112, v83, v112
	v_add_f32_e32 v112, v84, v112
	v_add_f32_e32 v112, v85, v112
	v_add_f32_e32 v112, v86, v112
	v_add_f32_e32 v112, v87, v112
	v_add_f32_e32 v112, v88, v112
	v_add_f32_e32 v112, v89, v112
	v_add_f32_e32 v112, v90, v112
	v_add_f32_e32 v112, v91, v112
	v_add_f32_e32 v112, v92, v112
	v_add_f32_e32 v112, v93, v112
	v_add_f32_e32 v112, v94, v112
	v_add_f32_e32 v112, v95, v112
	v_add_f32_e32 v112, v64, v112
	v_add_f32_e32 v112, v65, v112
	v_add_f32_e32 v112, v66, v112
	v_add_f32_e32 v112, v67, v112
	v_add_f32_e32 v112, v68, v112
	v_add_f32_e32 v112, v69, v112
	v_add_f32_e32 v112, v70, v112
	v_add_f32_e32 v112, v71, v112
	v_add_f32_e32 v112, v72, v112
	v_add_f32_e32 v112, v73, v112
	v_add_f32_e32 v112, v74, v112
	v_add_f32_e32 v112, v75, v112
	v_add_f32_e32 v112, v76, v112
	v_add_f32_e32 v112, v77, v112
	v_add_f32_e32 v112, v78, v112
	v_add_f32_e32 v112, v79, v112
	s_add_u32 s100, s42, s18
	s_addc_u32 s101, s43, 0
	s_add_i32 s18, s18, 0x4000
	s_and_b32 s18, s18, 0x1fffff
	s_add_u32 s98, s40, s18
	s_addc_u32 s99, s41, 0
	s_add_i32 s1, s24, s4
	s_add_i32 s25, s17, s4
	s_add_i32 m0, s1, 0xc000
	s_nop 0
	global_load_lds_dwordx4 v164, s[98:99]
	s_mov_b32 m0, s25
	s_nop 0
	global_load_lds_dwordx4 v166, s[100:101]
	s_add_i32 m0, s1, 0xc400
	s_nop 0
	global_load_lds_dwordx4 v168, s[98:99]
	s_add_i32 m0, s25, 0x400
	s_nop 0
	global_load_lds_dwordx4 v170, s[100:101]
	s_mov_b32 s1, s24
	s_mov_b32 s24, s0
	s_mov_b32 s0, s17
	s_mov_b32 s17, s1
	v_add_u32_e32 v215, s24, v195
	s_waitcnt lgkmcnt(0)
	s_barrier
.Lgqa_loop:
	s_setprio 1
	v_mfma_f32_32x32x16_bf16 v[80:95], v[146:149], v[138:141], 0
	ds_read_b64_tr_b16 v[146:147], v215 offset:0
	ds_read_b64_tr_b16 v[148:149], v215 offset:2048
	v_mfma_f32_32x32x16_bf16 v[64:79], v[150:153], v[138:141], 0
	ds_read_b64_tr_b16 v[150:151], v215 offset:4096
	ds_read_b64_tr_b16 v[152:153], v215 offset:6144
	v_mfma_f32_32x32x16_bf16 v[80:95], v[154:157], v[142:145], v[80:95]
	ds_read_b64_tr_b16 v[154:155], v215 offset:8192
	ds_read_b64_tr_b16 v[156:157], v215 offset:10240
	v_mfma_f32_32x32x16_bf16 v[64:79], v[158:161], v[142:145], v[64:79]
	ds_read_b64_tr_b16 v[158:159], v215 offset:12288
	ds_read_b64_tr_b16 v[160:161], v215 offset:14336
	v_mfma_f32_32x32x16_bf16 v[80:95], v[176:179], v[134:137], v[80:95]
	ds_read_b64_tr_b16 v[176:177], v215 offset:512
	ds_read_b64_tr_b16 v[178:179], v215 offset:2560
	v_mfma_f32_32x32x16_bf16 v[64:79], v[180:183], v[134:137], v[64:79]
	ds_read_b64_tr_b16 v[180:181], v215 offset:4608
	ds_read_b64_tr_b16 v[182:183], v215 offset:6656
	v_mfma_f32_32x32x16_bf16 v[80:95], v[216:219], v[114:117], v[80:95]
	ds_read_b64_tr_b16 v[216:217], v215 offset:8704
	ds_read_b64_tr_b16 v[218:219], v215 offset:10752
	v_mfma_f32_32x32x16_bf16 v[64:79], v[220:223], v[114:117], v[64:79]
	ds_read_b64_tr_b16 v[220:221], v215 offset:12800
	ds_read_b64_tr_b16 v[222:223], v215 offset:14848
	v_mfma_f32_32x32x16_bf16 v[80:95], v[224:227], v[118:121], v[80:95]
	ds_read_b64_tr_b16 v[224:225], v215 offset:1024
	ds_read_b64_tr_b16 v[226:227], v215 offset:3072
	v_mfma_f32_32x32x16_bf16 v[64:79], v[234:237], v[118:121], v[64:79]
	ds_read_b64_tr_b16 v[234:235], v215 offset:5120
	ds_read_b64_tr_b16 v[236:237], v215 offset:7168
	v_mfma_f32_32x32x16_bf16 v[80:95], v[240:243], v[122:125], v[80:95]
	ds_read_b64_tr_b16 v[240:241], v215 offset:9216
	ds_read_b64_tr_b16 v[242:243], v215 offset:11264
	v_mfma_f32_32x32x16_bf16 v[64:79], v[244:247], v[122:125], v[64:79]
	ds_read_b64_tr_b16 v[244:245], v215 offset:13312
	ds_read_b64_tr_b16 v[246:247], v215 offset:15360
	v_mfma_f32_32x32x16_bf16 v[80:95], v[248:251], v[126:129], v[80:95]
	ds_read_b64_tr_b16 v[248:249], v215 offset:1536
	ds_read_b64_tr_b16 v[250:251], v215 offset:3584
	v_mfma_f32_32x32x16_bf16 v[64:79], v[196:199], v[126:129], v[64:79]
	ds_read_b64_tr_b16 v[196:197], v215 offset:5632
	ds_read_b64_tr_b16 v[198:199], v215 offset:7680
	v_mfma_f32_32x32x16_bf16 v[80:95], v[206:209], v[130:133], v[80:95]
	ds_read_b64_tr_b16 v[206:207], v215 offset:9728
	ds_read_b64_tr_b16 v[208:209], v215 offset:11776
	v_mfma_f32_32x32x16_bf16 v[64:79], v[210:213], v[130:133], v[64:79]
	ds_read_b64_tr_b16 v[210:211], v215 offset:13824
	ds_read_b64_tr_b16 v[212:213], v215 offset:15872
	s_setprio 0
	s_barrier
; #define SBAR() __builtin_amdgcn_sched_barrier(0)
; #define NAM(P0, P1, t) do { if constexpr (NA) na_mask(P0, P1, kr_lo + (t), r0, qrow, qc, c0, hi, bl); } while (0)
; #define PSM(P0, P1, MN, AL) do { if constexpr (NA) partialSM(P0, P1, m_reg, MN, AL); else { AL = 1.f; _Pragma("unroll") for (int r = 0; r < 16; ++r) P0[r] = __builtin_amdgcn_exp2f(P0[r]); } } while (0)
; #define RESCN(a) do { if constexpr (NA) RESC(a); } while (0)
; #define VM0() asm volatile("s_waitcnt vmcnt(0)" ::: "memory")
; #define NAM(P0, P1, t) do { if constexpr (NA) na_mask(P0, P1, kr_lo + (t), r0, qrow, qc, c0, hi, bl); } while (0)
; #define RESCN(a) do { if constexpr (NA) RESC(a); } while (0)
; __device__ __forceinline__ void finishSM(f32x16& p0, f32x16& p1, float alpha, float& l_reg, bf16x8& pa0, bf16x8& pa1, bf16x8& pa2, bf16x8& pa3) {
;   for (int r = 0; r < 16; ++r) p1[r] = __builtin_amdgcn_exp2f(p1[r]);
;   float ps = 0; for (int r = 0; r < 16; ++r) ps += p0[r]; for (int r = 0; r < 16; ++r) ps += p1[r];
;   { auto rr = __builtin_amdgcn_permlane32_swap(__float_as_uint(ps), __float_as_uint(ps), false, false);
;     ps = __uint_as_float(rr[0]) + __uint_as_float(rr[1]); }
;   l_reg = l_reg * alpha + ps;
; template <bool NA, int ROWB>
; __device__ __forceinline__ void attn_dma(const bf16* __restrict__ Qb, const bf16* __restrict__ Kh, const bf16* __restrict__ Vh, bf16* __restrict__ Ob, int NT, char* lds, const int tid, float* __restrict__ ssb, int qrow0, int kr_lo, const float* bl) {
;     ...
;   for (int t = 1; t + 1 < NT; t += 2) {
;     DMA_TILE(t + 1, bn);
;     SBAR(); qkt<false>(pB0, pB1, (const bf16*)(K_lds + bc * SHM_K), qr, nullptr, r32, hi); NAM(pB0, pB1, t);
;     finishSM(pA0, pA1, alA, l_reg, pa0, pa1, pa2, pa3); SBAR();
;     pv_d0(o, vb0 + bp * (int)SHM_V, pa0, pa1, pa2, pa3); PSM(pB0, pB1, mnB, alB); RESCN(alB);
;     VM0(); __syncthreads();
;     bp = bc; bc = bn; bn = NEXTB(bn);
;     if (t + 2 < NT) DMA_TILE(t + 2, bn);
;     SBAR(); qkt<false>(pA0, pA1, (const bf16*)(K_lds + bc * SHM_K), qr, nullptr, r32, hi); NAM(pA0, pA1, t + 1);
;     finishSM(pB0, pB1, alB, l_reg, pa0, pa1, pa2, pa3); SBAR();
;     pv_d0(o, vb0 + bp * (int)SHM_V, pa0, pa1, pa2, pa3); PSM(pA0, pA1, mnA, alA); RESCN(alA);
;     VM0(); __syncthreads();
;     bp = bc; bc = bn; bn = NEXTB(bn);
;   }
	s_nop 7
	v_exp_f32_e32 v80, v80
	v_exp_f32_e32 v81, v81
	v_exp_f32_e32 v82, v82
	v_exp_f32_e32 v83, v83
	v_exp_f32_e32 v84, v84
	v_exp_f32_e32 v85, v85
	v_exp_f32_e32 v86, v86
	v_exp_f32_e32 v87, v87
	v_exp_f32_e32 v88, v88
	v_exp_f32_e32 v89, v89
	v_exp_f32_e32 v90, v90
	v_exp_f32_e32 v91, v91
	v_exp_f32_e32 v92, v92
	v_exp_f32_e32 v93, v93
	v_exp_f32_e32 v94, v94
	v_exp_f32_e32 v95, v95
	v_add_u32_e32 v229, s0, v187
	v_add_u32_e32 v230, s0, v188
	v_add_u32_e32 v232, s0, v189
	v_add_u32_e32 v238, s0, v190
	v_add_u32_e32 v203, s0, v191
	v_add_u32_e32 v205, s0, v192
	v_add_u32_e32 v214, s0, v193
	v_add_u32_e32 v175, s0, v194
	v_exp_f32_e32 v64, v64
	v_exp_f32_e32 v65, v65
	v_exp_f32_e32 v66, v66
	v_exp_f32_e32 v67, v67
	v_exp_f32_e32 v68, v68
	v_exp_f32_e32 v69, v69
	v_exp_f32_e32 v70, v70
	v_exp_f32_e32 v71, v71
	v_exp_f32_e32 v72, v72
	v_exp_f32_e32 v73, v73
	v_exp_f32_e32 v74, v74
	v_exp_f32_e32 v75, v75
	v_exp_f32_e32 v76, v76
	v_exp_f32_e32 v77, v77
	v_exp_f32_e32 v78, v78
	v_exp_f32_e32 v79, v79
	v_cvt_pk_bf16_f32 v96, v80, v81
	v_cvt_pk_bf16_f32 v97, v82, v83
	v_cvt_pk_bf16_f32 v98, v84, v85
	v_cvt_pk_bf16_f32 v99, v86, v87
	v_cvt_pk_bf16_f32 v100, v88, v89
	v_cvt_pk_bf16_f32 v101, v90, v91
	v_cvt_pk_bf16_f32 v102, v92, v93
	v_cvt_pk_bf16_f32 v103, v94, v95
	v_cvt_pk_bf16_f32 v104, v64, v65
	v_cvt_pk_bf16_f32 v105, v66, v67
	v_cvt_pk_bf16_f32 v106, v68, v69
	v_cvt_pk_bf16_f32 v107, v70, v71
	v_cvt_pk_bf16_f32 v108, v72, v73
	v_cvt_pk_bf16_f32 v109, v74, v75
	v_cvt_pk_bf16_f32 v110, v76, v77
	v_cvt_pk_bf16_f32 v111, v78, v79
	s_waitcnt lgkmcnt(0)
	s_barrier
	s_setprio 1
	v_mfma_f32_32x32x16_bf16 v[0:15], v[96:99], v[146:149], v[0:15]
	ds_read_b128 v[146:149], v229 offset:49152
	v_mfma_f32_32x32x16_bf16 v[0:15], v[100:103], v[150:153], v[0:15]
	ds_read_b128 v[150:153], v229 offset:57344
	v_mfma_f32_32x32x16_bf16 v[0:15], v[104:107], v[154:157], v[0:15]
	ds_read_b128 v[154:157], v230 offset:49152
	v_mfma_f32_32x32x16_bf16 v[0:15], v[108:111], v[158:161], v[0:15]
	ds_read_b128 v[158:161], v230 offset:57344
	v_mfma_f32_32x32x16_bf16 v[16:31], v[96:99], v[176:179], v[16:31]
	ds_read_b128 v[176:179], v232 offset:49152
	v_mfma_f32_32x32x16_bf16 v[16:31], v[100:103], v[180:183], v[16:31]
	ds_read_b128 v[180:183], v232 offset:57344
	v_mfma_f32_32x32x16_bf16 v[16:31], v[104:107], v[216:219], v[16:31]
	ds_read_b128 v[216:219], v238 offset:49152
	v_mfma_f32_32x32x16_bf16 v[16:31], v[108:111], v[220:223], v[16:31]
	ds_read_b128 v[220:223], v238 offset:57344
	v_mfma_f32_32x32x16_bf16 v[32:47], v[96:99], v[224:227], v[32:47]
	ds_read_b128 v[224:227], v203 offset:49152
	v_mfma_f32_32x32x16_bf16 v[32:47], v[100:103], v[234:237], v[32:47]
	ds_read_b128 v[234:237], v203 offset:57344
	v_mfma_f32_32x32x16_bf16 v[32:47], v[104:107], v[240:243], v[32:47]
	ds_read_b128 v[240:243], v205 offset:49152
	v_mfma_f32_32x32x16_bf16 v[32:47], v[108:111], v[244:247], v[32:47]
	ds_read_b128 v[244:247], v205 offset:57344
	v_mfma_f32_32x32x16_bf16 v[48:63], v[96:99], v[248:251], v[48:63]
	ds_read_b128 v[248:251], v214 offset:49152
	v_mfma_f32_32x32x16_bf16 v[48:63], v[100:103], v[196:199], v[48:63]
	ds_read_b128 v[196:199], v214 offset:57344
	v_mfma_f32_32x32x16_bf16 v[48:63], v[104:107], v[206:209], v[48:63]
	ds_read_b128 v[206:209], v175 offset:49152
	v_mfma_f32_32x32x16_bf16 v[48:63], v[108:111], v[210:213], v[48:63]
	ds_read_b128 v[210:213], v175 offset:57344
	s_setprio 0
	s_waitcnt vmcnt(0)
	s_barrier
	v_add_f32_e32 v112, v80, v112
	v_add_f32_e32 v112, v81, v112
	v_add_f32_e32 v112, v82, v112
	v_add_f32_e32 v112, v83, v112
	v_add_f32_e32 v112, v84, v112
	v_add_f32_e32 v112, v85, v112
	v_add_f32_e32 v112, v86, v112
	v_add_f32_e32 v112, v87, v112
	v_add_f32_e32 v112, v88, v112
	v_add_f32_e32 v112, v89, v112
	v_add_f32_e32 v112, v90, v112
	v_add_f32_e32 v112, v91, v112
	v_add_f32_e32 v112, v92, v112
	v_add_f32_e32 v112, v93, v112
	v_add_f32_e32 v112, v94, v112
	v_add_f32_e32 v112, v95, v112
	v_add_f32_e32 v112, v64, v112
	v_add_f32_e32 v112, v65, v112
	v_add_f32_e32 v112, v66, v112
	v_add_f32_e32 v112, v67, v112
	v_add_f32_e32 v112, v68, v112
	v_add_f32_e32 v112, v69, v112
	v_add_f32_e32 v112, v70, v112
	v_add_f32_e32 v112, v71, v112
	v_add_f32_e32 v112, v72, v112
	v_add_f32_e32 v112, v73, v112
	v_add_f32_e32 v112, v74, v112
	v_add_f32_e32 v112, v75, v112
	v_add_f32_e32 v112, v76, v112
	v_add_f32_e32 v112, v77, v112
	v_add_f32_e32 v112, v78, v112
	v_add_f32_e32 v112, v79, v112
	s_add_u32 s100, s42, s18
	s_addc_u32 s101, s43, 0
	s_add_i32 s18, s18, 0x4000
	s_and_b32 s18, s18, 0x1fffff
	s_add_u32 s98, s40, s18
	s_addc_u32 s99, s41, 0
	s_add_i32 s1, s24, s4
	s_add_i32 s25, s17, s4
	s_add_i32 m0, s1, 0xc000
	s_nop 0
	global_load_lds_dwordx4 v164, s[98:99]
	s_mov_b32 m0, s25
	s_nop 0
	global_load_lds_dwordx4 v166, s[100:101]
	s_add_i32 m0, s1, 0xc400
	s_nop 0
	global_load_lds_dwordx4 v168, s[98:99]
	s_add_i32 m0, s25, 0x400
	s_nop 0
	global_load_lds_dwordx4 v170, s[100:101]
	s_mov_b32 s1, s24
	s_mov_b32 s24, s0
	s_mov_b32 s0, s17
	s_mov_b32 s17, s1
	v_add_u32_e32 v215, s24, v195
	s_waitcnt lgkmcnt(0)
	s_barrier
	s_add_i32 s16, s16, 1
	s_cmp_eq_u32 s16, 125
	s_cbranch_scc0 .Lgqa_loop
	s_setprio 1
	v_mfma_f32_32x32x16_bf16 v[80:95], v[146:149], v[138:141], 0
	v_mfma_f32_32x32x16_bf16 v[64:79], v[150:153], v[138:141], 0
	v_mfma_f32_32x32x16_bf16 v[80:95], v[154:157], v[142:145], v[80:95]
	v_mfma_f32_32x32x16_bf16 v[64:79], v[158:161], v[142:145], v[64:79]
	v_mfma_f32_32x32x16_bf16 v[80:95], v[176:179], v[134:137], v[80:95]
	v_mfma_f32_32x32x16_bf16 v[64:79], v[180:183], v[134:137], v[64:79]
	v_mfma_f32_32x32x16_bf16 v[80:95], v[216:219], v[114:117], v[80:95]
	v_mfma_f32_32x32x16_bf16 v[64:79], v[220:223], v[114:117], v[64:79]
	v_mfma_f32_32x32x16_bf16 v[80:95], v[224:227], v[118:121], v[80:95]
	v_mfma_f32_32x32x16_bf16 v[64:79], v[234:237], v[118:121], v[64:79]
	v_mfma_f32_32x32x16_bf16 v[80:95], v[240:243], v[122:125], v[80:95]
	v_mfma_f32_32x32x16_bf16 v[64:79], v[244:247], v[122:125], v[64:79]
	v_mfma_f32_32x32x16_bf16 v[80:95], v[248:251], v[126:129], v[80:95]
	v_mfma_f32_32x32x16_bf16 v[64:79], v[196:199], v[126:129], v[64:79]
	v_mfma_f32_32x32x16_bf16 v[80:95], v[206:209], v[130:133], v[80:95]
	v_mfma_f32_32x32x16_bf16 v[64:79], v[210:213], v[130:133], v[64:79]
	s_setprio 0
	s_waitcnt vmcnt(0)
	s_barrier
	s_cmp_ge_u32 s4, 0x2000
	s_cbranch_scc1 .Lgqa_trail
	s_barrier
; #define SBAR() __builtin_amdgcn_sched_barrier(0)
; #define NAM(P0, P1, t) do { if constexpr (NA) na_mask(P0, P1, kr_lo + (t), r0, qrow, qc, c0, hi, bl); } while (0)
; #define PSM(P0, P1, MN, AL) do { if constexpr (NA) partialSM(P0, P1, m_reg, MN, AL); else { AL = 1.f; _Pragma("unroll") for (int r = 0; r < 16; ++r) P0[r] = __builtin_amdgcn_exp2f(P0[r]); } } while (0)
; #define RESCN(a) do { if constexpr (NA) RESC(a); } while (0)
; #define NAM(P0, P1, t) do { if constexpr (NA) na_mask(P0, P1, kr_lo + (t), r0, qrow, qc, c0, hi, bl); } while (0)
; #define PSM(P0, P1, MN, AL) do { if constexpr (NA) partialSM(P0, P1, m_reg, MN, AL); else { AL = 1.f; _Pragma("unroll") for (int r = 0; r < 16; ++r) P0[r] = __builtin_amdgcn_exp2f(P0[r]); } } while (0)
; #define RESCN(a) do { if constexpr (NA) RESC(a); } while (0)
; __device__ __forceinline__ void finishSM(f32x16& p0, f32x16& p1, float alpha, float& l_reg, bf16x8& pa0, bf16x8& pa1, bf16x8& pa2, bf16x8& pa3) {
;   for (int r = 0; r < 16; ++r) p1[r] = __builtin_amdgcn_exp2f(p1[r]);
;   float ps = 0; for (int r = 0; r < 16; ++r) ps += p0[r]; for (int r = 0; r < 16; ++r) ps += p1[r];
;   { auto rr = __builtin_amdgcn_permlane32_swap(__float_as_uint(ps), __float_as_uint(ps), false, false);
;     ps = __uint_as_float(rr[0]) + __uint_as_float(rr[1]); }
;   l_reg = l_reg * alpha + ps;
;     ...
;   PK4(p0, 0, pa0); PK4(p0, 8, pa1); PK4(p1, 0, pa2); PK4(p1, 8, pa3);
; template <bool NA, int ROWB>
; __device__ __forceinline__ void attn_dma(const bf16* __restrict__ Qb, const bf16* __restrict__ Kh, const bf16* __restrict__ Vh, bf16* __restrict__ Ob, int NT, char* lds, const int tid, float* __restrict__ ssb, int qrow0, int kr_lo, const float* bl) {
;     ...
;   SBAR(); qkt<false>(pB0, pB1, (const bf16*)(K_lds + bc * SHM_K), qr, nullptr, r32, hi); NAM(pB0, pB1, NT - 1);
;   finishSM(pA0, pA1, alA, l_reg, pa0, pa1, pa2, pa3); SBAR();
;   pv_d0(o, vb0 + bp * (int)SHM_V, pa0, pa1, pa2, pa3); PSM(pB0, pB1, mnB, alB); RESCN(alB);
;   finishSM(pB0, pB1, alB, l_reg, pa0, pa1, pa2, pa3); SBAR();
.Lgqa_trail:
	s_nop 15
	v_exp_f32_e32 v212, v80
	v_exp_f32_e32 v214, v81
	v_exp_f32_e32 v210, v82
	v_exp_f32_e32 v213, v83
	v_exp_f32_e32 v208, v84
	v_exp_f32_e32 v211, v85
	v_exp_f32_e32 v207, v86
	v_exp_f32_e32 v209, v87
	v_exp_f32_e32 v203, v88
	v_exp_f32_e32 v206, v89
	v_exp_f32_e32 v198, v90
	v_exp_f32_e32 v205, v91
	v_exp_f32_e32 v196, v92
	v_exp_f32_e32 v199, v93
	v_exp_f32_e32 v175, v94
	v_exp_f32_e32 v197, v95
	v_exp_f32_e32 v64, v64
	v_exp_f32_e32 v65, v65
	v_exp_f32_e32 v66, v66
	v_exp_f32_e32 v67, v67
	v_exp_f32_e32 v68, v68
	v_exp_f32_e32 v69, v69
	v_exp_f32_e32 v70, v70
	v_exp_f32_e32 v71, v71
	v_exp_f32_e32 v72, v72
	v_exp_f32_e32 v73, v73
	v_exp_f32_e32 v74, v74
	v_exp_f32_e32 v75, v75
	v_exp_f32_e32 v76, v76
	v_exp_f32_e32 v77, v77
	v_exp_f32_e32 v78, v78
	v_exp_f32_e32 v79, v79
	v_mov_b32_e32 v228, v112
	s_nop 1
	v_permlane32_swap_b32_e32 v112, v228
	v_add_f32_e32 v112, v112, v228
	s_add_i32 s0, 0, 0x10000
	v_add_u32_e32 v84, s0, v187
	ds_read_b128 v[80:83], v84
	ds_read_b128 v[154:157], v84 offset:8192
	v_add_u32_e32 v100, s0, v188
	ds_read_b128 v[96:99], v100
	ds_read_b128 v[158:161], v100 offset:8192
	v_add_u32_e32 v100, s0, v189
	s_waitcnt lgkmcnt(3)
	v_mfma_f32_32x32x16_bf16 v[80:95], v[80:83], v[138:141], 0
	s_nop 0
	v_mov_b32_e32 v180, v66
	v_mov_b32_e32 v181, v67
	v_mov_b32_e32 v182, v68
	v_mov_b32_e32 v183, v69
	v_mov_b32_e32 v215, v70
	v_mov_b32_e32 v216, v71
	v_mov_b32_e32 v217, v72
	s_waitcnt lgkmcnt(1)
	v_mfma_f32_32x32x16_bf16 v[80:95], v[96:99], v[142:145], v[80:95]
	ds_read_b128 v[96:99], v100
	ds_read_b128 v[150:153], v100 offset:8192
	v_mov_b32_e32 v218, v73
	v_mov_b32_e32 v219, v74
	v_mov_b32_e32 v220, v75
	v_mov_b32_e32 v221, v76
	v_mov_b32_e32 v222, v77
	v_mov_b32_e32 v223, v78
	s_waitcnt lgkmcnt(1)
	v_mfma_f32_32x32x16_bf16 v[80:95], v[96:99], v[134:137], v[80:95]
	v_add_u32_e32 v96, s0, v190
	ds_read_b128 v[100:103], v96
	ds_read_b128 v[96:99], v96 offset:8192
	v_mov_b32_e32 v79, v79
	s_waitcnt lgkmcnt(1)
	v_mfma_f32_32x32x16_bf16 v[80:95], v[100:103], v[114:117], v[80:95]
	v_add_u32_e32 v100, s0, v191
	ds_read_b128 v[104:107], v100
	ds_read_b128 v[100:103], v100 offset:8192
	s_waitcnt lgkmcnt(1)
	v_mfma_f32_32x32x16_bf16 v[80:95], v[104:107], v[118:121], v[80:95]
	v_add_u32_e32 v104, s0, v192
	ds_read_b128 v[108:111], v104
	ds_read_b128 v[104:107], v104 offset:8192
	s_waitcnt lgkmcnt(1)
	v_mfma_f32_32x32x16_bf16 v[80:95], v[108:111], v[122:125], v[80:95]
	v_add_u32_e32 v108, s0, v193
	ds_read_b128 v[146:149], v108
	ds_read_b128 v[108:111], v108 offset:8192
	s_waitcnt lgkmcnt(1)
	v_mfma_f32_32x32x16_bf16 v[80:95], v[146:149], v[126:129], v[80:95]
	v_add_u32_e32 v146, s0, v194
	ds_read_b128 v[176:179], v146
	ds_read_b128 v[146:149], v146 offset:8192
	s_waitcnt lgkmcnt(1)
	v_mfma_f32_32x32x16_bf16 v[80:95], v[176:179], v[130:133], v[80:95]
	v_mov_b32_e32 v177, v64
	v_add_f32_e32 v64, 0, v212
	v_add_f32_e32 v64, v214, v64
	v_add_f32_e32 v64, v210, v64
	v_add_f32_e32 v64, v213, v64
	v_add_f32_e32 v64, v208, v64
	v_add_f32_e32 v64, v211, v64
	v_add_f32_e32 v64, v207, v64
	v_add_f32_e32 v64, v209, v64
	v_add_f32_e32 v64, v203, v64
	v_add_f32_e32 v64, v206, v64
	v_add_f32_e32 v64, v198, v64
	v_add_f32_e32 v64, v205, v64
	v_add_f32_e32 v64, v196, v64
	v_mov_b32_e32 v179, v65
	v_add_f32_e32 v64, v199, v64
	v_add_f32_e32 v64, v175, v64
	v_add_f32_e32 v64, v197, v64
	v_add_f32_e32 v64, v64, v177
	v_add_f32_e32 v64, v179, v64
	v_add_f32_e32 v64, v180, v64
	v_add_f32_e32 v64, v181, v64
	v_add_f32_e32 v64, v182, v64
	v_add_f32_e32 v64, v183, v64
	v_add_f32_e32 v64, v215, v64
	v_add_f32_e32 v64, v216, v64
	v_add_f32_e32 v64, v217, v64
	v_add_f32_e32 v64, v218, v64
	v_add_f32_e32 v64, v219, v64
	v_add_f32_e32 v64, v220, v64
	v_add_f32_e32 v64, v221, v64
	v_add_f32_e32 v64, v222, v64
	v_add_f32_e32 v64, v223, v64
	v_add_f32_e32 v176, v79, v64
	v_mov_b32_e32 v178, v176
	s_nop 1
	v_permlane32_swap_b32_e32 v176, v178
	v_cvt_pk_bf16_f32 v64, v212, v214
	v_cvt_pk_bf16_f32 v65, v210, v213
	v_cvt_pk_bf16_f32 v66, v208, v211
	v_cvt_pk_bf16_f32 v67, v207, v209
	v_cvt_pk_bf16_f32 v68, v203, v206
	v_cvt_pk_bf16_f32 v69, v198, v205
	v_cvt_pk_bf16_f32 v70, v196, v199
	v_cvt_pk_bf16_f32 v71, v175, v197
	v_cvt_pk_bf16_f32 v72, v177, v179
	v_cvt_pk_bf16_f32 v73, v180, v181
	v_cvt_pk_bf16_f32 v74, v182, v183
	v_cvt_pk_bf16_f32 v75, v215, v216
	v_cvt_pk_bf16_f32 v76, v217, v218
	v_cvt_pk_bf16_f32 v77, v219, v220
	v_cvt_pk_bf16_f32 v78, v221, v222
	v_cvt_pk_bf16_f32 v79, v223, v79
	s_nop 0
	ds_read_b64_tr_b16 v[180:181], v195 offset:0
	ds_read_b64_tr_b16 v[182:183], v195 offset:0x800
	ds_read_b64_tr_b16 v[196:197], v195 offset:0x1000
	ds_read_b64_tr_b16 v[198:199], v195 offset:0x1800
	ds_read_b64_tr_b16 v[206:207], v195 offset:0x2000
	ds_read_b64_tr_b16 v[208:209], v195 offset:0x2800
	ds_read_b64_tr_b16 v[210:211], v195 offset:0x3000
	ds_read_b64_tr_b16 v[212:213], v195 offset:0x3800
	s_waitcnt lgkmcnt(0)
	s_nop 0
	v_mfma_f32_32x32x16_bf16 v[0:15], v[64:67], v[180:183], v[0:15]
	ds_read_b64_tr_b16 v[180:181], v195 offset:0x200
	ds_read_b64_tr_b16 v[182:183], v195 offset:0xa00
	v_mfma_f32_32x32x16_bf16 v[0:15], v[68:71], v[196:199], v[0:15]
	ds_read_b64_tr_b16 v[196:197], v195 offset:0x1200
	ds_read_b64_tr_b16 v[198:199], v195 offset:0x1a00
	v_mfma_f32_32x32x16_bf16 v[0:15], v[72:75], v[206:209], v[0:15]
	ds_read_b64_tr_b16 v[206:207], v195 offset:0x2200
	ds_read_b64_tr_b16 v[208:209], v195 offset:0x2a00
	v_mfma_f32_32x32x16_bf16 v[0:15], v[76:79], v[210:213], v[0:15]
	ds_read_b64_tr_b16 v[210:211], v195 offset:0x3200
	ds_read_b64_tr_b16 v[212:213], v195 offset:0x3a00
	s_waitcnt lgkmcnt(0)
; #define SBAR() __builtin_amdgcn_sched_barrier(0)
; #define NAM(P0, P1, t) do { if constexpr (NA) na_mask(P0, P1, kr_lo + (t), r0, qrow, qc, c0, hi, bl); } while (0)
; #define PSM(P0, P1, MN, AL) do { if constexpr (NA) partialSM(P0, P1, m_reg, MN, AL); else { AL = 1.f; _Pragma("unroll") for (int r = 0; r < 16; ++r) P0[r] = __builtin_amdgcn_exp2f(P0[r]); } } while (0)
; #define RESCN(a) do { if constexpr (NA) RESC(a); } while (0)
; #define NAM(P0, P1, t) do { if constexpr (NA) na_mask(P0, P1, kr_lo + (t), r0, qrow, qc, c0, hi, bl); } while (0)
; #define PSM(P0, P1, MN, AL) do { if constexpr (NA) partialSM(P0, P1, m_reg, MN, AL); else { AL = 1.f; _Pragma("unroll") for (int r = 0; r < 16; ++r) P0[r] = __builtin_amdgcn_exp2f(P0[r]); } } while (0)
; #define RESCN(a) do { if constexpr (NA) RESC(a); } while (0)
; __device__ __forceinline__ void finishSM(f32x16& p0, f32x16& p1, float alpha, float& l_reg, bf16x8& pa0, bf16x8& pa1, bf16x8& pa2, bf16x8& pa3) {
;   for (int r = 0; r < 16; ++r) p1[r] = __builtin_amdgcn_exp2f(p1[r]);
;   float ps = 0; for (int r = 0; r < 16; ++r) ps += p0[r]; for (int r = 0; r < 16; ++r) ps += p1[r];
;   { auto rr = __builtin_amdgcn_permlane32_swap(__float_as_uint(ps), __float_as_uint(ps), false, false);
;     ps = __uint_as_float(rr[0]) + __uint_as_float(rr[1]); }
;   l_reg = l_reg * alpha + ps;
;     ...
;   PK4(p0, 0, pa0); PK4(p0, 8, pa1); PK4(p1, 0, pa2); PK4(p1, 8, pa3);
; template <bool NA, int ROWB>
; __device__ __forceinline__ void attn_dma(const bf16* __restrict__ Qb, const bf16* __restrict__ Kh, const bf16* __restrict__ Vh, bf16* __restrict__ Ob, int NT, char* lds, const int tid, float* __restrict__ ssb, int qrow0, int kr_lo, const float* bl) {
;     ...
;   SBAR(); qkt<false>(pB0, pB1, (const bf16*)(K_lds + bc * SHM_K), qr, nullptr, r32, hi); NAM(pB0, pB1, NT - 1);
;   finishSM(pA0, pA1, alA, l_reg, pa0, pa1, pa2, pa3); SBAR();
;   pv_d0(o, vb0 + bp * (int)SHM_V, pa0, pa1, pa2, pa3); PSM(pB0, pB1, mnB, alB); RESCN(alB);
;   finishSM(pB0, pB1, alB, l_reg, pa0, pa1, pa2, pa3); SBAR();
;   pv_d0(o, vb0 + bc * (int)SHM_V, pa0, pa1, pa2, pa3);
	v_mfma_f32_32x32x16_bf16 v[16:31], v[64:67], v[180:183], v[16:31]
	ds_read_b64_tr_b16 v[180:181], v195 offset:0x400
	ds_read_b64_tr_b16 v[182:183], v195 offset:0xc00
	v_mfma_f32_32x32x16_bf16 v[16:31], v[68:71], v[196:199], v[16:31]
	ds_read_b64_tr_b16 v[196:197], v195 offset:0x1400
	ds_read_b64_tr_b16 v[198:199], v195 offset:0x1c00
	v_mfma_f32_32x32x16_bf16 v[16:31], v[72:75], v[206:209], v[16:31]
	ds_read_b64_tr_b16 v[206:207], v195 offset:0x2400
	ds_read_b64_tr_b16 v[208:209], v195 offset:0x2c00
	v_mfma_f32_32x32x16_bf16 v[16:31], v[76:79], v[210:213], v[16:31]
	ds_read_b64_tr_b16 v[210:211], v195 offset:0x3400
	ds_read_b64_tr_b16 v[212:213], v195 offset:0x3c00
	s_waitcnt lgkmcnt(0)
	v_mfma_f32_32x32x16_bf16 v[32:47], v[64:67], v[180:183], v[32:47]
	ds_read_b64_tr_b16 v[180:181], v195 offset:0x600
	ds_read_b64_tr_b16 v[182:183], v195 offset:0xe00
	v_mfma_f32_32x32x16_bf16 v[32:47], v[68:71], v[196:199], v[32:47]
	ds_read_b64_tr_b16 v[196:197], v195 offset:0x1600
	ds_read_b64_tr_b16 v[198:199], v195 offset:0x1e00
	v_mfma_f32_32x32x16_bf16 v[32:47], v[72:75], v[206:209], v[32:47]
	ds_read_b64_tr_b16 v[206:207], v195 offset:0x2600
	ds_read_b64_tr_b16 v[208:209], v195 offset:0x2e00
	v_mfma_f32_32x32x16_bf16 v[32:47], v[76:79], v[210:213], v[32:47]
	ds_read_b64_tr_b16 v[210:211], v195 offset:0x3600
	ds_read_b64_tr_b16 v[212:213], v195 offset:0x3e00
	s_waitcnt lgkmcnt(0)
	v_mfma_f32_32x32x16_bf16 v[48:63], v[64:67], v[180:183], v[48:63]
	v_exp_f32_e32 v175, v80
	v_exp_f32_e32 v180, v81
	v_exp_f32_e32 v181, v82
	v_exp_f32_e32 v182, v83
	v_exp_f32_e32 v183, v84
	v_exp_f32_e32 v80, v90
	v_exp_f32_e32 v86, v86
	v_mfma_f32_32x32x16_bf16 v[48:63], v[68:71], v[196:199], v[48:63]
	v_exp_f32_e32 v196, v85
	v_exp_f32_e32 v87, v87
	v_exp_f32_e32 v88, v88
	v_exp_f32_e32 v89, v89
	v_exp_f32_e32 v81, v91
	v_exp_f32_e32 v82, v92
	v_exp_f32_e32 v83, v93
	v_mfma_f32_32x32x16_bf16 v[48:63], v[72:75], v[206:209], v[48:63]
	v_exp_f32_e32 v84, v94
	v_exp_f32_e32 v85, v95
	v_mfma_f32_32x32x16_bf16 v[48:63], v[76:79], v[210:213], v[48:63]
	v_mfma_f32_32x32x16_bf16 v[64:79], v[154:157], v[138:141], 0
	v_mfma_f32_32x32x16_bf16 v[64:79], v[158:161], v[142:145], v[64:79]
	v_mfma_f32_32x32x16_bf16 v[64:79], v[150:153], v[134:137], v[64:79]
	v_mfma_f32_32x32x16_bf16 v[64:79], v[96:99], v[114:117], v[64:79]
	v_mfma_f32_32x32x16_bf16 v[64:79], v[100:103], v[118:121], v[64:79]
	v_mfma_f32_32x32x16_bf16 v[64:79], v[104:107], v[122:125], v[64:79]
	v_mfma_f32_32x32x16_bf16 v[64:79], v[108:111], v[126:129], v[64:79]
	s_waitcnt lgkmcnt(0)
	v_mfma_f32_32x32x16_bf16 v[64:79], v[146:149], v[130:133], v[64:79]
	s_nop 11
	v_exp_f32_e32 v90, v64
	v_add_f32_e32 v64, 0, v175
	v_add_f32_e32 v64, v180, v64
	v_add_f32_e32 v64, v181, v64
	v_add_f32_e32 v64, v182, v64
	v_add_f32_e32 v64, v183, v64
	v_add_f32_e32 v64, v196, v64
	v_add_f32_e32 v64, v86, v64
	v_add_f32_e32 v64, v87, v64
	v_add_f32_e32 v64, v88, v64
	v_add_f32_e32 v64, v89, v64
	v_add_f32_e32 v64, v80, v64
	v_add_f32_e32 v64, v81, v64
	v_add_f32_e32 v64, v82, v64
	v_exp_f32_e32 v91, v65
	v_add_f32_e32 v64, v83, v64
	v_exp_f32_e32 v92, v66
	v_add_f32_e32 v64, v84, v64
	v_exp_f32_e32 v93, v67
	v_add_f32_e32 v64, v85, v64
	v_exp_f32_e32 v94, v68
	v_add_f32_e32 v64, v64, v90
	v_exp_f32_e32 v95, v69
	v_add_f32_e32 v64, v91, v64
	v_exp_f32_e32 v96, v70
	v_add_f32_e32 v64, v92, v64
	v_exp_f32_e32 v97, v71
	v_add_f32_e32 v64, v93, v64
	v_exp_f32_e32 v98, v72
	v_add_f32_e32 v64, v94, v64
	v_exp_f32_e32 v99, v73
	v_add_f32_e32 v64, v95, v64
	v_exp_f32_e32 v100, v74
	v_add_f32_e32 v64, v96, v64
	v_exp_f32_e32 v101, v75
	v_add_f32_e32 v64, v97, v64
	v_exp_f32_e32 v102, v76
	v_add_f32_e32 v64, v98, v64
	v_exp_f32_e32 v103, v77
	v_add_f32_e32 v64, v99, v64
	v_exp_f32_e32 v104, v78
	v_add_f32_e32 v64, v100, v64
	v_exp_f32_e32 v79, v79
	v_add_f32_e32 v64, v101, v64
	v_add_f32_e32 v64, v102, v64
	v_add_f32_e32 v64, v103, v64
	v_add_f32_e32 v64, v104, v64
	v_add_f32_e32 v177, v79, v64
	v_mov_b32_e32 v179, v177
	s_nop 1
	v_permlane32_swap_b32_e32 v177, v179
	v_cvt_pk_bf16_f32 v64, v175, v180
	v_cvt_pk_bf16_f32 v65, v181, v182
	v_cvt_pk_bf16_f32 v66, v183, v196
	v_cvt_pk_bf16_f32 v67, v86, v87
	v_cvt_pk_bf16_f32 v68, v88, v89
	v_cvt_pk_bf16_f32 v69, v80, v81
	v_cvt_pk_bf16_f32 v70, v82, v83
	v_cvt_pk_bf16_f32 v71, v84, v85
	v_cvt_pk_bf16_f32 v72, v90, v91
	v_cvt_pk_bf16_f32 v73, v92, v93
	v_cvt_pk_bf16_f32 v74, v94, v95
	v_cvt_pk_bf16_f32 v75, v96, v97
	v_cvt_pk_bf16_f32 v76, v98, v99
	v_cvt_pk_bf16_f32 v77, v100, v101
	v_cvt_pk_bf16_f32 v78, v102, v103
	v_cvt_pk_bf16_f32 v79, v104, v79
	s_nop 0
	ds_read_b64_tr_b16 v[80:81], v201 offset:0
	ds_read_b64_tr_b16 v[82:83], v201 offset:0x800
	ds_read_b64_tr_b16 v[84:85], v201 offset:0x1000
	ds_read_b64_tr_b16 v[86:87], v201 offset:0x1800
	ds_read_b64_tr_b16 v[88:89], v201 offset:0x2000
	ds_read_b64_tr_b16 v[90:91], v201 offset:0x2800
	ds_read_b64_tr_b16 v[92:93], v201 offset:0x3000
	ds_read_b64_tr_b16 v[94:95], v201 offset:0x3800
	s_waitcnt lgkmcnt(0)
	s_nop 0
	v_mfma_f32_32x32x16_bf16 v[0:15], v[64:67], v[80:83], v[0:15]
	ds_read_b64_tr_b16 v[80:81], v201 offset:0x200
	ds_read_b64_tr_b16 v[82:83], v201 offset:0xa00
	v_mfma_f32_32x32x16_bf16 v[0:15], v[68:71], v[84:87], v[0:15]
	ds_read_b64_tr_b16 v[84:85], v201 offset:0x1200
	ds_read_b64_tr_b16 v[86:87], v201 offset:0x1a00
	v_mfma_f32_32x32x16_bf16 v[0:15], v[72:75], v[88:91], v[0:15]
	ds_read_b64_tr_b16 v[88:89], v201 offset:0x2200
	ds_read_b64_tr_b16 v[90:91], v201 offset:0x2a00
	v_mfma_f32_32x32x16_bf16 v[0:15], v[76:79], v[92:95], v[0:15]
	ds_read_b64_tr_b16 v[92:93], v201 offset:0x3200
	ds_read_b64_tr_b16 v[94:95], v201 offset:0x3a00
	s_waitcnt lgkmcnt(0)
; __device__ __forceinline__ int crow(int r, int hi) { return (r & 3) + 8 * (r >> 2) + 4 * hi; }
; template <bool NA, int ROWB>
; __device__ __forceinline__ void attn_dma(const bf16* __restrict__ Qb, const bf16* __restrict__ Kh, const bf16* __restrict__ Vh, bf16* __restrict__ Ob, int NT, char* lds, const int tid, float* __restrict__ ssb, int qrow0, int kr_lo, const float* bl) {
;     ...
;   pv_d0(o, vb0 + bc * (int)SHM_V, pa0, pa1, pa2, pa3);
;   if (hi == 0) li_l[r32] = l_reg; asm volatile("s_waitcnt lgkmcnt(0)" ::: "memory");
;   float rli[16];
; #pragma unroll
;   for (int r = 0; r < 16; ++r) rli[r] = __builtin_amdgcn_rcpf(li_l[crow(r, hi)]);
	v_mfma_f32_32x32x16_bf16 v[16:31], v[64:67], v[80:83], v[16:31]
	ds_read_b64_tr_b16 v[80:81], v201 offset:0x400
	ds_read_b64_tr_b16 v[82:83], v201 offset:0xc00
	v_mfma_f32_32x32x16_bf16 v[16:31], v[68:71], v[84:87], v[16:31]
	ds_read_b64_tr_b16 v[84:85], v201 offset:0x1400
	ds_read_b64_tr_b16 v[86:87], v201 offset:0x1c00
	v_mfma_f32_32x32x16_bf16 v[16:31], v[72:75], v[88:91], v[16:31]
	ds_read_b64_tr_b16 v[88:89], v201 offset:0x2400
	ds_read_b64_tr_b16 v[90:91], v201 offset:0x2c00
	v_mfma_f32_32x32x16_bf16 v[16:31], v[76:79], v[92:95], v[16:31]
	ds_read_b64_tr_b16 v[92:93], v201 offset:0x3400
	ds_read_b64_tr_b16 v[94:95], v201 offset:0x3c00
	s_waitcnt lgkmcnt(0)
	v_mfma_f32_32x32x16_bf16 v[32:47], v[64:67], v[80:83], v[32:47]
	ds_read_b64_tr_b16 v[80:81], v201 offset:0x600
	ds_read_b64_tr_b16 v[82:83], v201 offset:0xe00
	v_mfma_f32_32x32x16_bf16 v[32:47], v[68:71], v[84:87], v[32:47]
	ds_read_b64_tr_b16 v[84:85], v201 offset:0x1600
	ds_read_b64_tr_b16 v[86:87], v201 offset:0x1e00
	v_mfma_f32_32x32x16_bf16 v[32:47], v[72:75], v[88:91], v[32:47]
	ds_read_b64_tr_b16 v[88:89], v201 offset:0x2600
	ds_read_b64_tr_b16 v[90:91], v201 offset:0x2e00
	v_mfma_f32_32x32x16_bf16 v[32:47], v[76:79], v[92:95], v[32:47]
	ds_read_b64_tr_b16 v[92:93], v201 offset:0x3600
	ds_read_b64_tr_b16 v[94:95], v201 offset:0x3e00
	s_waitcnt lgkmcnt(0)
	v_mfma_f32_32x32x16_bf16 v[48:63], v[64:67], v[80:83], v[48:63]
	v_mfma_f32_32x32x16_bf16 v[48:63], v[68:71], v[84:87], v[48:63]
	v_mfma_f32_32x32x16_bf16 v[48:63], v[72:75], v[88:91], v[48:63]
	v_mfma_f32_32x32x16_bf16 v[48:63], v[76:79], v[92:95], v[48:63]
	s_and_saveexec_b64 s[4:5], vcc
	v_pk_add_f32 v[64:65], v[176:177], v[178:179]
	s_nop 0
	v_add_f32_e32 v64, v112, v64
	v_add_f32_e32 v64, v64, v65
	ds_write_b32 v204, v64
	s_or_b64 exec, exec, s[4:5]
	s_lshl_b64 s[0:1], s[6:7], 12
	v_readlane_b32 s4, v254, 41
	s_waitcnt lgkmcnt(0)
	v_add_u32_e32 v72, v185, v186
	s_add_u32 s4, s4, s0
	v_readlane_b32 s0, v254, 42
	ds_read_b128 v[64:67], v72
	ds_read_b128 v[68:71], v72 offset:32
	s_addc_u32 s5, s0, s1
	s_lshl_b64 s[0:1], s[6:7], 6
	v_readlane_b32 s6, v254, 32
	v_readlane_b32 s7, v254, 33
	s_add_u32 s6, s6, s0
	s_addc_u32 s7, s7, s1
	s_lshl_b32 s0, s15, 1
	s_add_u32 s0, s4, s0
	s_waitcnt lgkmcnt(1)
	v_rcp_f32_e32 v84, v64
	s_addc_u32 s1, s5, 0
	v_mov_b32_e32 v74, v200
	v_rcp_f32_e32 v85, v65
	v_rcp_f32_e32 v86, v66
	v_rcp_f32_e32 v87, v67
	s_waitcnt lgkmcnt(0)
; __device__ __forceinline__ float xs(float v, int o, int lane) { return __int_as_float(__builtin_amdgcn_ds_bpermute((lane ^ o) << 2, __float_as_int(v))); }
; __device__ __forceinline__ void st16_wt(void* p, u32x4 v) { asm volatile("global_store_dwordx4 %0, %1, off sc0 sc1\n\ts_nop 1" :: "v"(p), "v"(v) : "memory"); }
; template <bool NA, int ROWB>
; __device__ __forceinline__ void attn_dma(const bf16* __restrict__ Qb, const bf16* __restrict__ Kh, const bf16* __restrict__ Vh, bf16* __restrict__ Ob, int NT, char* lds, const int tid, float* __restrict__ ssb, int qrow0, int kr_lo, const float* bl) {
;     ...
;   int tid_e = tid; asm volatile("" : "+v"(tid_e));
;   const int lane_e = tid_e & 63, wid_e = tid_e >> 6, r32_e = lane_e & 31, hi_e = lane_e >> 5;
;   char* sg = lds + 100 * 1024 + wid_e * 4096;
; #pragma unroll
;   for (int half = 0; half < 2; ++half) {
;     char* wb_e = sg + hi_e * 1024 + r32_e * 2 + hi_e * 64;
;     char* wb_o = sg + hi_e * 1024 + r32_e * 2 - hi_e * 64;
; #pragma unroll
;     for (int rr = 0; rr < 8; ++rr) { const int r = half * 8 + rr; const int rc = ((rr & 3) + 8 * (rr >> 2)) * 256;
; #pragma unroll
;       for (int d0 = 0; d0 < 4; ++d0) { const float v = o[d0][r] * rli[r]; *(bf16*)(((d0 & 1) ? wb_o : wb_e) + rc + d0 * 64) = (bf16)(cvtpk(v, v) & 0xffffu); } }
;     asm volatile("s_waitcnt lgkmcnt(0)" ::: "memory");
;     const char* rb_e = sg + (lane_e >> 4) * 256 + (lane_e & 15) * 16;
;     const char* rb_o = sg + (lane_e >> 4) * 256 + (((lane_e & 15) * 16) ^ 64);
;     bf16* gb = Ow + (long)(half * 16 + (lane_e >> 4)) * LDO + (lane_e & 15) * 8;
; #pragma unroll
;     for (int i = 0; i < 4; ++i) { const u32x4 w = *(const u32x4*)(((i & 1) ? rb_o : rb_e) + i * 1024); st16_wt(gb + (long)i * 4 * LDO, w);
;       float q = sumsq8(w); q += xs(q, 1, lane_e); q += xs(q, 2, lane_e); q += xs(q, 4, lane_e); q += xs(q, 8, lane_e);
;       if ((lane_e & 15) == 0) ssb[(size_t)(wid_e * QBLK + half * 16 + (lane_e >> 4) + 4 * i) * 16] = q; }
	v_rcp_f32_e32 v88, v68
	v_rcp_f32_e32 v89, v69
	v_rcp_f32_e32 v90, v70
	v_rcp_f32_e32 v91, v71
	ds_read_b128 v[68:71], v72 offset:64
	ds_read_b128 v[64:67], v72 offset:96
	v_lshl_add_u64 v[72:73], s[0:1], 0, v[172:173]
	v_readlane_b32 s0, v254, 20
	v_ashrrev_i32_e32 v78, 6, v74
	v_bfe_u32 v76, v74, 5, 1
	v_lshlrev_b32_e32 v80, 1, v74
	v_and_b32_e32 v93, 15, v74
	v_and_b32_e32 v75, 63, v74
	v_lshl_add_u32 v77, v78, 12, s0
	v_lshlrev_b32_e32 v79, 10, v76
	v_and_b32_e32 v80, 62, v80
	v_lshlrev_b32_e32 v112, 4, v93
	v_add3_u32 v79, v77, v79, v80
	v_lshlrev_b32_e32 v80, 6, v76
	v_bfe_u32 v92, v74, 4, 2
	v_lshl_add_u64 v[82:83], v[72:73], 0, v[112:113]
	v_lshlrev_b32_e32 v72, 2, v75
	v_mul_f32_e32 v0, v0, v84
	v_lshl_add_u32 v81, v92, 8, v77
	v_xor_b32_e32 v77, 4, v72
	v_xor_b32_e32 v76, 8, v72
	v_xor_b32_e32 v75, 16, v72
	v_xor_b32_e32 v74, 32, v72
	v_lshl_or_b32 v72, v78, 5, v92
	v_cvt_pk_bf16_f32 v0, v0, v0
	v_add_u32_e32 v78, v79, v80
	ds_write_b16 v78, v0
	v_mul_f32_e32 v0, v16, v84
	v_cvt_pk_bf16_f32 v0, v0, v0
	v_sub_u32_e32 v16, v79, v80
	ds_write_b16 v16, v0 offset:64
	v_mul_f32_e32 v0, v32, v84
	v_cvt_pk_bf16_f32 v0, v0, v0
	ds_write_b16 v78, v0 offset:128
	v_mul_f32_e32 v0, v48, v84
	v_cvt_pk_bf16_f32 v0, v0, v0
	ds_write_b16 v16, v0 offset:192
	v_mul_f32_e32 v0, v1, v85
	v_cvt_pk_bf16_f32 v0, v0, v0
	ds_write_b16 v78, v0 offset:256
	v_mul_f32_e32 v0, v17, v85
	v_cvt_pk_bf16_f32 v0, v0, v0
	ds_write_b16 v16, v0 offset:320
	v_mul_f32_e32 v0, v33, v85
	v_cvt_pk_bf16_f32 v0, v0, v0
	ds_write_b16 v78, v0 offset:384
	v_mul_f32_e32 v0, v49, v85
	v_cvt_pk_bf16_f32 v0, v0, v0
	ds_write_b16 v16, v0 offset:448
	v_mul_f32_e32 v0, v2, v86
	v_cvt_pk_bf16_f32 v0, v0, v0
	ds_write_b16 v78, v0 offset:512
	v_mul_f32_e32 v0, v18, v86
	v_cvt_pk_bf16_f32 v0, v0, v0
	ds_write_b16 v16, v0 offset:576
	v_mul_f32_e32 v0, v34, v86
	v_cvt_pk_bf16_f32 v0, v0, v0
	ds_write_b16 v78, v0 offset:640
	v_mul_f32_e32 v0, v50, v86
	v_cvt_pk_bf16_f32 v0, v0, v0
	ds_write_b16 v16, v0 offset:704
	v_mul_f32_e32 v0, v3, v87
	v_cvt_pk_bf16_f32 v0, v0, v0
	ds_write_b16 v78, v0 offset:768
	v_mul_f32_e32 v0, v19, v87
	v_cvt_pk_bf16_f32 v0, v0, v0
	ds_write_b16 v16, v0 offset:832
	v_mul_f32_e32 v0, v35, v87
	v_cvt_pk_bf16_f32 v0, v0, v0
	ds_write_b16 v78, v0 offset:896
	v_mul_f32_e32 v0, v51, v87
	v_cvt_pk_bf16_f32 v0, v0, v0
	ds_write_b16 v16, v0 offset:960
	v_mul_f32_e32 v0, v4, v88
	v_cvt_pk_bf16_f32 v0, v0, v0
	ds_write_b16 v78, v0 offset:2048
	v_mul_f32_e32 v0, v20, v88
	v_cvt_pk_bf16_f32 v0, v0, v0
	ds_write_b16 v16, v0 offset:2112
	v_mul_f32_e32 v0, v36, v88
	v_cvt_pk_bf16_f32 v0, v0, v0
	ds_write_b16 v78, v0 offset:2176
	v_mul_f32_e32 v0, v52, v88
	v_cvt_pk_bf16_f32 v0, v0, v0
	ds_write_b16 v16, v0 offset:2240
	v_mul_f32_e32 v0, v5, v89
	v_cvt_pk_bf16_f32 v0, v0, v0
	ds_write_b16 v78, v0 offset:2304
	v_mul_f32_e32 v0, v21, v89
	v_cvt_pk_bf16_f32 v0, v0, v0
	ds_write_b16 v16, v0 offset:2368
	v_mul_f32_e32 v0, v37, v89
	v_cvt_pk_bf16_f32 v0, v0, v0
	ds_write_b16 v78, v0 offset:2432
	v_mul_f32_e32 v0, v53, v89
	v_cvt_pk_bf16_f32 v0, v0, v0
	ds_write_b16 v16, v0 offset:2496
	v_mul_f32_e32 v0, v6, v90
	v_cvt_pk_bf16_f32 v0, v0, v0
	ds_write_b16 v78, v0 offset:2560
	v_mul_f32_e32 v0, v22, v90
	v_cvt_pk_bf16_f32 v0, v0, v0
	ds_write_b16 v16, v0 offset:2624
	v_mul_f32_e32 v0, v38, v90
	v_cvt_pk_bf16_f32 v0, v0, v0
	ds_write_b16 v78, v0 offset:2688
	v_mul_f32_e32 v0, v54, v90
	v_cvt_pk_bf16_f32 v0, v0, v0
	ds_write_b16 v16, v0 offset:2752
	v_mul_f32_e32 v0, v7, v91
	v_cvt_pk_bf16_f32 v0, v0, v0
	ds_write_b16 v78, v0 offset:2816
	v_mul_f32_e32 v0, v23, v91
	v_cvt_pk_bf16_f32 v0, v0, v0
	ds_write_b16 v16, v0 offset:2880
	v_mul_f32_e32 v0, v39, v91
	v_cvt_pk_bf16_f32 v0, v0, v0
	ds_write_b16 v78, v0 offset:2944
	v_mul_f32_e32 v0, v55, v91
	v_cvt_pk_bf16_f32 v0, v0, v0
	ds_write_b16 v16, v0 offset:3008
	s_waitcnt lgkmcnt(0)
	v_add_u32_e32 v2, v81, v112
	ds_read_b128 v[4:7], v2
	v_lshlrev_b32_e32 v0, 12, v92
	v_mov_b32_e32 v1, v113
	v_lshl_add_u64 v[0:1], v[82:83], 0, v[0:1]
	s_mov_b64 s[0:1], 0x800
	v_lshl_add_u64 v[0:1], v[0:1], 0, s[0:1]
	s_waitcnt lgkmcnt(0)
	global_store_dwordx4 v[0:1], v[4:7], off sc0 sc1
	s_nop 1
	v_lshlrev_b32_e32 v3, 16, v4
	v_and_b32_e32 v4, 0xffff0000, v4
	v_mul_f32_e32 v4, v4, v4
	v_fmac_f32_e32 v4, v3, v3
	v_lshlrev_b32_e32 v3, 16, v5
	v_and_b32_e32 v5, 0xffff0000, v5
	v_mul_f32_e32 v5, v5, v5
	v_fmac_f32_e32 v5, v3, v3
	v_add_f32_e32 v3, v4, v5
	v_and_b32_e32 v5, 0xffff0000, v6
	v_lshlrev_b32_e32 v4, 16, v6
	v_mul_f32_e32 v5, v5, v5
	v_fmac_f32_e32 v5, v4, v4
	v_add_f32_e32 v3, v5, v3
	v_and_b32_e32 v5, 0xffff0000, v7
	v_lshlrev_b32_e32 v4, 16, v7
	v_mul_f32_e32 v5, v5, v5
	v_fmac_f32_e32 v5, v4, v4
	v_add_f32_e32 v3, v5, v3
	ds_bpermute_b32 v4, v77, v3
	s_lshl_b32 s4, s14, 2
	s_add_u32 s4, s6, s4
	s_addc_u32 s5, s7, 0
	s_add_u32 s6, s4, 0x25cc0020
	s_waitcnt lgkmcnt(0)
	v_add_f32_e32 v3, v3, v4
	ds_bpermute_b32 v4, v76, v3
	s_addc_u32 s7, s5, 0
	v_cmp_eq_u32_e64 s[4:5], 0, v93
	s_waitcnt lgkmcnt(0)
	v_add_f32_e32 v3, v3, v4
	ds_bpermute_b32 v4, v75, v3
	s_waitcnt lgkmcnt(0)
	v_add_f32_e32 v3, v3, v4
	ds_bpermute_b32 v4, v74, v3
	s_and_saveexec_b64 s[14:15], s[4:5]
	v_readlane_b32 s16, v254, 47
	v_readlane_b32 s28, v254, 34
	s_mov_b32 s36, s38
	v_readlane_b32 s17, v254, 48
	v_readlane_b32 s29, v254, 35
	s_cbranch_execz .LBB0_111
	v_ashrrev_i32_e32 v73, 31, v72
	v_lshlrev_b64 v[6:7], 6, v[72:73]
	v_lshl_add_u64 v[6:7], s[6:7], 0, v[6:7]
	s_waitcnt lgkmcnt(0)
	v_add_f32_e32 v3, v3, v4
	global_store_dword v[6:7], v3, off
